# in-proj epilogue QK-norm reductions: xor16/xor32 steps via v_permlane16/32_swap instead of ds_bpermute
# speedup vs baseline: 1.0132x; 1.0010x over previous
.LBB0_286:
	v_mov_b32_e32 v130, s88
	v_mov_b32_e32 v131, s89
	ds_read_b32 v130, v130
	ds_read_b32 v131, v131
	s_lshl_b32 s57, s3, 8
	s_add_i32 s57, s57, s10
	s_waitcnt lgkmcnt(0)
	v_readfirstlane_b32 s21, v130
	v_readfirstlane_b32 s20, v131
	v_mov_b32_e32 v130, s93
	v_mov_b32_e32 v131, s94
	ds_read_b32 v130, v130
	ds_read_b32 v131, v131
	v_or_b32_e32 v186, s57, v1
	s_cmp_lg_u32 s1, 0
	s_waitcnt lgkmcnt(0)
	v_readfirstlane_b32 s36, v130
	v_readfirstlane_b32 s59, v131
	v_mov_b32_e32 v130, s95
	v_mov_b32_e32 v131, s96
	ds_read_b32 v130, v130
	ds_read_b32 v131, v131
	s_waitcnt lgkmcnt(0)
	v_readfirstlane_b32 s46, v130
	v_readfirstlane_b32 s37, v131
	v_mov_b32_e32 v130, s97
	v_mov_b32_e32 v131, s28
	ds_read_b32 v130, v130
	ds_read_b32 v131, v131
	s_waitcnt lgkmcnt(0)
	v_readfirstlane_b32 s83, v130
	v_readfirstlane_b32 s82, v131
	ds_read_b128 v[142:145], v205 offset:512
	ds_read_b128 v[138:141], v205 offset:528
	ds_read_b128 v[134:137], v205 offset:544
	ds_read_b128 v[130:133], v205 offset:560
	ds_read2_b32 v[146:147], v203 offset1:16
	s_waitcnt lgkmcnt(0)
	v_fmamk_f32 v146, v146, 0x3a800000, v229
	v_cmp_gt_f32_e32 vcc, s92, v146
	v_mul_f32_e32 v148, 0x4b800000, v146
	s_nop 0
	v_cndmask_b32_e32 v146, v146, v148, vcc
	v_rsq_f32_e32 v146, v146
	s_nop 0
	v_mul_f32_e32 v148, 0x45800000, v146
	v_cndmask_b32_e32 v146, v146, v148, vcc
	v_pk_fma_f32 v[4:5], v[4:5], v[146:147], v[144:145] op_sel_hi:[1,0,1]
	v_pk_fma_f32 v[2:3], v[2:3], v[146:147], v[142:143] op_sel_hi:[1,0,1]
	v_pk_fma_f32 v[8:9], v[8:9], v[146:147], v[140:141] op_sel_hi:[1,0,1]
	v_pk_fma_f32 v[6:7], v[6:7], v[146:147], v[138:139] op_sel_hi:[1,0,1]
	v_pk_fma_f32 v[16:17], v[16:17], v[146:147], v[136:137] op_sel_hi:[1,0,1]
	v_pk_fma_f32 v[14:15], v[14:15], v[146:147], v[134:135] op_sel_hi:[1,0,1]
	v_pk_fma_f32 v[12:13], v[12:13], v[146:147], v[132:133] op_sel_hi:[1,0,1]
	v_pk_fma_f32 v[10:11], v[10:11], v[146:147], v[130:131] op_sel_hi:[1,0,1]
	v_fmamk_f32 v146, v147, 0x3a800000, v229
	v_cmp_gt_f32_e32 vcc, s92, v146
	v_mul_f32_e32 v147, 0x4b800000, v146
	s_nop 0
	v_cndmask_b32_e32 v146, v146, v147, vcc
	v_rsq_f32_e32 v146, v146
	s_nop 0
	v_mul_f32_e32 v147, 0x45800000, v146
	v_cndmask_b32_e32 v146, v146, v147, vcc
	v_pk_fma_f32 v[32:33], v[32:33], v[146:147], v[144:145] op_sel_hi:[1,0,1]
	v_pk_fma_f32 v[30:31], v[30:31], v[146:147], v[142:143] op_sel_hi:[1,0,1]
	v_pk_fma_f32 v[28:29], v[28:29], v[146:147], v[140:141] op_sel_hi:[1,0,1]
	v_pk_fma_f32 v[26:27], v[26:27], v[146:147], v[138:139] op_sel_hi:[1,0,1]
	v_pk_fma_f32 v[24:25], v[24:25], v[146:147], v[136:137] op_sel_hi:[1,0,1]
	v_pk_fma_f32 v[22:23], v[22:23], v[146:147], v[134:135] op_sel_hi:[1,0,1]
	v_pk_fma_f32 v[20:21], v[20:21], v[146:147], v[132:133] op_sel_hi:[1,0,1]
	v_pk_fma_f32 v[18:19], v[18:19], v[146:147], v[130:131] op_sel_hi:[1,0,1]
	ds_read2_b32 v[146:147], v203 offset0:32 offset1:48
	s_waitcnt lgkmcnt(0)
	v_fmamk_f32 v146, v146, 0x3a800000, v229
	v_cmp_gt_f32_e32 vcc, s92, v146
	v_mul_f32_e32 v148, 0x4b800000, v146
	s_nop 0
	v_cndmask_b32_e32 v146, v146, v148, vcc
	v_rsq_f32_e32 v146, v146
	s_nop 0
	v_mul_f32_e32 v148, 0x45800000, v146
	v_cndmask_b32_e32 v146, v146, v148, vcc
	v_pk_fma_f32 v[36:37], v[36:37], v[146:147], v[144:145] op_sel_hi:[1,0,1]
	v_pk_fma_f32 v[34:35], v[34:35], v[146:147], v[142:143] op_sel_hi:[1,0,1]
	v_pk_fma_f32 v[44:45], v[44:45], v[146:147], v[140:141] op_sel_hi:[1,0,1]
	v_pk_fma_f32 v[42:43], v[42:43], v[146:147], v[138:139] op_sel_hi:[1,0,1]
	v_pk_fma_f32 v[48:49], v[48:49], v[146:147], v[136:137] op_sel_hi:[1,0,1]
	v_pk_fma_f32 v[46:47], v[46:47], v[146:147], v[134:135] op_sel_hi:[1,0,1]
	v_pk_fma_f32 v[40:41], v[40:41], v[146:147], v[132:133] op_sel_hi:[1,0,1]
	v_pk_fma_f32 v[38:39], v[38:39], v[146:147], v[130:131] op_sel_hi:[1,0,1]
	v_fmamk_f32 v146, v147, 0x3a800000, v229
	v_cmp_gt_f32_e32 vcc, s92, v146
	v_mul_f32_e32 v147, 0x4b800000, v146
	s_nop 0
	v_cndmask_b32_e32 v146, v146, v147, vcc
	v_rsq_f32_e32 v146, v146
	s_nop 0
	v_mul_f32_e32 v147, 0x45800000, v146
	v_cndmask_b32_e32 v146, v146, v147, vcc
	v_pk_fma_f32 v[64:65], v[64:65], v[146:147], v[144:145] op_sel_hi:[1,0,1]
	v_pk_fma_f32 v[62:63], v[62:63], v[146:147], v[142:143] op_sel_hi:[1,0,1]
	v_pk_fma_f32 v[60:61], v[60:61], v[146:147], v[140:141] op_sel_hi:[1,0,1]
	v_pk_fma_f32 v[58:59], v[58:59], v[146:147], v[138:139] op_sel_hi:[1,0,1]
	v_pk_fma_f32 v[56:57], v[56:57], v[146:147], v[136:137] op_sel_hi:[1,0,1]
	v_pk_fma_f32 v[54:55], v[54:55], v[146:147], v[134:135] op_sel_hi:[1,0,1]
	v_pk_fma_f32 v[52:53], v[52:53], v[146:147], v[132:133] op_sel_hi:[1,0,1]
	v_pk_fma_f32 v[50:51], v[50:51], v[146:147], v[130:131] op_sel_hi:[1,0,1]
	ds_read2_b32 v[146:147], v203 offset0:64 offset1:80
	s_waitcnt lgkmcnt(0)
	v_fmamk_f32 v146, v146, 0x3a800000, v229
	v_cmp_gt_f32_e32 vcc, s92, v146
	v_mul_f32_e32 v148, 0x4b800000, v146
	s_nop 0
	v_cndmask_b32_e32 v146, v146, v148, vcc
	v_rsq_f32_e32 v146, v146
	s_nop 0
	v_mul_f32_e32 v148, 0x45800000, v146
	v_cndmask_b32_e32 v146, v146, v148, vcc
	v_pk_fma_f32 v[76:77], v[76:77], v[146:147], v[144:145] op_sel_hi:[1,0,1]
	v_pk_fma_f32 v[74:75], v[74:75], v[146:147], v[142:143] op_sel_hi:[1,0,1]
	v_pk_fma_f32 v[72:73], v[72:73], v[146:147], v[140:141] op_sel_hi:[1,0,1]
	v_pk_fma_f32 v[70:71], v[70:71], v[146:147], v[138:139] op_sel_hi:[1,0,1]
	v_pk_fma_f32 v[80:81], v[80:81], v[146:147], v[136:137] op_sel_hi:[1,0,1]
	v_pk_fma_f32 v[78:79], v[78:79], v[146:147], v[134:135] op_sel_hi:[1,0,1]
	v_pk_fma_f32 v[68:69], v[68:69], v[146:147], v[132:133] op_sel_hi:[1,0,1]
	v_pk_fma_f32 v[66:67], v[66:67], v[146:147], v[130:131] op_sel_hi:[1,0,1]
	v_fmamk_f32 v146, v147, 0x3a800000, v229
	v_cmp_gt_f32_e32 vcc, s92, v146
	v_mul_f32_e32 v147, 0x4b800000, v146
	s_nop 0
	v_cndmask_b32_e32 v146, v146, v147, vcc
	v_rsq_f32_e32 v146, v146
	s_nop 0
	v_mul_f32_e32 v147, 0x45800000, v146
	v_cndmask_b32_e32 v146, v146, v147, vcc
	v_pk_fma_f32 v[96:97], v[96:97], v[146:147], v[144:145] op_sel_hi:[1,0,1]
	v_pk_fma_f32 v[94:95], v[94:95], v[146:147], v[142:143] op_sel_hi:[1,0,1]
	v_pk_fma_f32 v[92:93], v[92:93], v[146:147], v[140:141] op_sel_hi:[1,0,1]
	v_pk_fma_f32 v[90:91], v[90:91], v[146:147], v[138:139] op_sel_hi:[1,0,1]
	v_pk_fma_f32 v[88:89], v[88:89], v[146:147], v[136:137] op_sel_hi:[1,0,1]
	v_pk_fma_f32 v[86:87], v[86:87], v[146:147], v[134:135] op_sel_hi:[1,0,1]
	v_pk_fma_f32 v[84:85], v[84:85], v[146:147], v[132:133] op_sel_hi:[1,0,1]
	v_pk_fma_f32 v[82:83], v[82:83], v[146:147], v[130:131] op_sel_hi:[1,0,1]
	ds_read2_b32 v[146:147], v203 offset0:96 offset1:112
	s_waitcnt lgkmcnt(0)
	v_fmamk_f32 v146, v146, 0x3a800000, v229
	v_cmp_gt_f32_e32 vcc, s92, v146
	v_mul_f32_e32 v148, 0x4b800000, v146
	s_nop 0
	v_cndmask_b32_e32 v146, v146, v148, vcc
	v_rsq_f32_e32 v146, v146
	s_nop 0
	v_mul_f32_e32 v148, 0x45800000, v146
	v_cndmask_b32_e32 v146, v146, v148, vcc
	v_pk_fma_f32 v[108:109], v[108:109], v[146:147], v[144:145] op_sel_hi:[1,0,1]
	v_pk_fma_f32 v[106:107], v[106:107], v[146:147], v[142:143] op_sel_hi:[1,0,1]
	v_pk_fma_f32 v[104:105], v[104:105], v[146:147], v[140:141] op_sel_hi:[1,0,1]
	v_pk_fma_f32 v[102:103], v[102:103], v[146:147], v[138:139] op_sel_hi:[1,0,1]
	v_pk_fma_f32 v[112:113], v[112:113], v[146:147], v[136:137] op_sel_hi:[1,0,1]
	v_pk_fma_f32 v[110:111], v[110:111], v[146:147], v[134:135] op_sel_hi:[1,0,1]
	v_pk_fma_f32 v[100:101], v[100:101], v[146:147], v[132:133] op_sel_hi:[1,0,1]
	v_pk_fma_f32 v[98:99], v[98:99], v[146:147], v[130:131] op_sel_hi:[1,0,1]
	v_fmamk_f32 v146, v147, 0x3a800000, v229
	v_cmp_gt_f32_e32 vcc, s92, v146
	v_mul_f32_e32 v147, 0x4b800000, v146
	s_nop 0
	v_cndmask_b32_e32 v146, v146, v147, vcc
	v_rsq_f32_e32 v146, v146
	s_nop 0
	v_mul_f32_e32 v147, 0x45800000, v146
	v_cndmask_b32_e32 v146, v146, v147, vcc
	v_pk_fma_f32 v[120:121], v[120:121], v[146:147], v[144:145] op_sel_hi:[1,0,1]
	v_pk_fma_f32 v[118:119], v[118:119], v[146:147], v[142:143] op_sel_hi:[1,0,1]
	v_pk_fma_f32 v[116:117], v[116:117], v[146:147], v[140:141] op_sel_hi:[1,0,1]
	v_pk_fma_f32 v[114:115], v[114:115], v[146:147], v[138:139] op_sel_hi:[1,0,1]
	v_pk_fma_f32 v[124:125], v[124:125], v[146:147], v[136:137] op_sel_hi:[1,0,1]
	v_pk_fma_f32 v[122:123], v[122:123], v[146:147], v[134:135] op_sel_hi:[1,0,1]
	v_pk_fma_f32 v[128:129], v[128:129], v[146:147], v[132:133] op_sel_hi:[1,0,1]
	v_pk_fma_f32 v[126:127], v[126:127], v[146:147], v[130:131] op_sel_hi:[1,0,1]
	s_cbranch_scc0 .LBB0_395
	s_cmp_gt_i32 s1, 2
	s_mov_b64 s[4:5], -1
	s_cbranch_scc0 .LBB0_388
	s_cmp_lt_i32 s3, 32
	s_cselect_b64 s[4:5], -1, 0
	s_cmp_gt_i32 s3, 31
	s_cselect_b64 s[68:69], -1, 0
	s_cmp_eq_u32 s1, 5
	s_cselect_b64 s[84:85], -1, 0
	s_and_b64 vcc, s[84:85], s[50:51]
	s_mov_b64 s[6:7], -1
	s_andn2_b64 vcc, exec, vcc
	v_lshlrev_b32_e32 v188, 2, v178
	s_cbranch_vccz .LBB0_322
	s_and_b64 s[6:7], s[84:85], exec
	s_cselect_b32 s6, s83, s46
	v_readlane_b32 s0, v255, 34
	s_cselect_b32 s3, s82, s37
	s_add_u32 s6, s6, s0
	s_addc_u32 s7, s3, 0
	global_load_dwordx4 v[142:145], v188, s[6:7]
	global_load_dwordx4 v[138:141], v188, s[6:7] offset:64
	global_load_dwordx4 v[134:137], v188, s[6:7] offset:128
	global_load_dwordx4 v[130:133], v188, s[6:7] offset:192
	v_cmp_lt_i32_e32 vcc, v227, v222
	v_pk_mul_f32 v[146:147], v[4:5], v[4:5]
	v_pk_mul_f32 v[148:149], v[2:3], v[2:3]
	v_pk_mul_f32 v[150:151], v[8:9], v[8:9]
	v_pk_mul_f32 v[152:153], v[6:7], v[6:7]
	v_cndmask_b32_e32 v155, v221, v227, vcc
	v_cmp_lt_i32_e32 vcc, v228, v222
	v_pk_mov_b32 v[158:159], v[148:149], v[146:147] op_sel:[1,0]
	v_mov_b32_e32 v149, v147
	v_pk_mov_b32 v[146:147], v[152:153], v[150:151] op_sel:[1,0]
	v_mov_b32_e32 v153, v151
	v_cndmask_b32_e32 v157, v221, v228, vcc
	v_mul_f32_e32 v154, v14, v14
	v_mul_f32_e32 v156, v16, v16
	v_pk_add_f32 v[148:149], v[158:159], v[148:149]
	v_pk_add_f32 v[146:147], v[146:147], v[152:153]
	v_lshlrev_b32_e32 v169, 2, v155
	v_pk_fma_f32 v[150:151], v[14:15], v[14:15], v[154:155] op_sel_hi:[1,1,0]
	v_pk_fma_f32 v[154:155], v[16:17], v[16:17], v[156:157] op_sel_hi:[1,1,0]
	v_pk_add_f32 v[148:149], v[148:149], v[148:149] op_sel_hi:[0,1]
	v_pk_add_f32 v[146:147], v[146:147], v[146:147] op_sel_hi:[0,1]
	v_mul_f32_e32 v150, v10, v10
	v_mul_f32_e32 v154, v11, v11
	v_mul_f32_e32 v148, v12, v12
	v_mul_f32_e32 v146, v13, v13
	v_pk_add_f32 v[150:151], v[150:151], v[154:155]
	v_pk_add_f32 v[146:147], v[148:149], v[146:147]
	v_lshlrev_b32_e32 v167, 2, v157
	v_pk_add_f32 v[146:147], v[150:151], v[146:147]
	s_lshl_b32 s3, s38, 2
	v_add_f32_e32 v146, v146, v147
	v_mov_b32_e32 v147, v146
	s_nop 1
	v_permlane16_swap_b32_e32 v147, v146
	s_and_b64 s[6:7], s[84:85], s[4:5]
	s_add_u32 s82, s36, s3
	v_mov_b32_e32 v189, v0
	s_addc_u32 s83, s59, 0
	s_waitcnt lgkmcnt(0)
	v_add_f32_e32 v148, v146, v147
	v_mov_b32_e32 v149, v148
	s_nop 1
	v_permlane32_swap_b32_e32 v149, v148
	v_cndmask_b32_e64 v152, 0, 1, s[6:7]
	s_andn2_b64 vcc, exec, s[6:7]
	v_lshl_add_u64 v[146:147], s[82:83], 0, v[188:189]
	s_mov_b64 s[6:7], 0x6000000
	v_lshl_add_u64 v[194:195], v[146:147], 0, s[6:7]
	s_waitcnt lgkmcnt(0)
	v_add_f32_e32 v147, v148, v149
	v_fmamk_f32 v147, v147, 0x3c800000, v229
	v_mul_f32_e32 v148, 0x4b800000, v147
	v_cmp_gt_f32_e64 s[6:7], s92, v147
	s_ashr_i32 s3, s57, 7
	s_and_b32 s3, s3, -2
	v_cndmask_b32_e64 v147, v147, v148, s[6:7]
	v_rsq_f32_e32 v148, v147
	v_or_b32_e32 v146, s3, v179
	v_ashrrev_i32_e32 v147, 31, v146
	v_lshlrev_b64 v[146:147], 17, v[146:147]
	v_lshl_add_u64 v[196:197], v[194:195], 0, v[146:147]
	v_mul_f32_e32 v146, 0x45800000, v148
	v_cndmask_b32_e64 v146, v148, v146, s[6:7]
	v_cmp_ne_u32_e64 s[4:5], 1, v152
	v_pk_mul_f32 v[148:149], v[2:3], v[146:147] op_sel_hi:[1,0]
	v_pk_mul_f32 v[150:151], v[4:5], v[146:147] op_sel_hi:[1,0]
	v_pk_mul_f32 v[152:153], v[6:7], v[146:147] op_sel_hi:[1,0]
	v_pk_mul_f32 v[154:155], v[8:9], v[146:147] op_sel_hi:[1,0]
	v_pk_mul_f32 v[190:191], v[14:15], v[146:147] op_sel_hi:[1,0]
	v_pk_mul_f32 v[192:193], v[16:17], v[146:147] op_sel_hi:[1,0]
	v_pk_mul_f32 v[198:199], v[10:11], v[146:147] op_sel_hi:[1,0]
	v_pk_mul_f32 v[146:147], v[12:13], v[146:147] op_sel_hi:[1,0]
	s_waitcnt vmcnt(0)
	v_pk_mul_f32 v[160:161], v[144:145], v[150:151]
	v_pk_mul_f32 v[158:159], v[142:143], v[148:149]
	v_pk_mul_f32 v[156:157], v[140:141], v[154:155]
	v_pk_mul_f32 v[154:155], v[138:139], v[152:153]
	v_pk_mul_f32 v[152:153], v[136:137], v[192:193]
	v_pk_mul_f32 v[150:151], v[134:135], v[190:191]
	v_pk_mul_f32 v[148:149], v[132:133], v[146:147]
	v_pk_mul_f32 v[146:147], v[130:131], v[198:199]
	s_cbranch_vccnz .LBB0_291
	v_lshlrev_b32_e32 v171, 9, v186
	v_and_b32_e32 v190, 0x19e00, v171
	v_mov_b32_e32 v191, v0
	v_lshl_add_u64 v[190:191], v[196:197], 0, v[190:191]
	global_store_dwordx4 v[190:191], v[158:161], off nt
	global_store_dwordx4 v[190:191], v[154:157], off offset:64 nt
	global_store_dwordx4 v[190:191], v[150:153], off offset:128 nt
	global_store_dwordx4 v[190:191], v[146:149], off offset:192 nt

.LBB0_293:
	s_lshl_b32 s37, s1, 8
	v_readlane_b32 s0, v255, 33
	s_add_i32 s46, s0, s37
	s_lshl_b64 vcc, s[46:47], 1
	s_add_u32 s37, s21, vcc_lo
	s_addc_u32 s46, s20, vcc_hi
	s_add_u32 vcc_lo, s37, 0x9800000
	s_addc_u32 s46, s46, 0
	s_lshl_b32 s37, s38, 1
	s_add_u32 s37, s21, s37
	s_addc_u32 vcc_hi, s20, 0
	s_add_u32 s0, s37, 0xb000000
	v_mov_b32_e32 v173, 0x3e38aa3b
	s_addc_u32 vcc_hi, vcc_hi, 0
	v_cndmask_b32_e64 v190, v173, 1.0, s[84:85]
	s_and_b64 s[84:85], s[84:85], exec
	v_ashrrev_i32_e32 v187, 31, v186
	s_cselect_b32 s37, 8, 10
	s_cselect_b32 s85, vcc_hi, s46
	s_cselect_b32 s84, s0, vcc_lo
	v_lshlrev_b32_e32 v192, 1, v178
	v_mov_b32_e32 v193, v0
	v_lshl_add_u64 v[192:193], s[84:85], 0, v[192:193]
	v_lshlrev_b64 v[198:199], s37, v[186:187]
	v_pk_mul_f32 v[148:149], v[190:191], v[148:149] op_sel_hi:[0,1]
	v_pk_mul_f32 v[146:147], v[190:191], v[146:147] op_sel_hi:[0,1]
	v_lshl_add_u64 v[198:199], v[192:193], 0, v[198:199]
	v_pk_mul_f32 v[152:153], v[190:191], v[152:153] op_sel_hi:[0,1]
	v_pk_mul_f32 v[150:151], v[190:191], v[150:151] op_sel_hi:[0,1]
	v_cvt_pk_bf16_f32 v146, v146, v147
	v_cvt_pk_bf16_f32 v147, v148, v149
	v_cvt_pk_bf16_f32 v150, v150, v151
	v_cvt_pk_bf16_f32 v151, v152, v153
	global_store_dwordx2 v[198:199], v[146:147], off offset:96
	v_pk_mul_f32 v[146:147], v[32:33], v[32:33]
	v_pk_mul_f32 v[148:149], v[30:31], v[30:31]
	global_store_dwordx2 v[198:199], v[150:151], off offset:64
	v_pk_mov_b32 v[150:151], v[148:149], v[146:147] op_sel:[1,0]
	v_mov_b32_e32 v149, v147
	v_pk_add_f32 v[146:147], v[150:151], v[148:149]
	v_pk_mul_f32 v[148:149], v[28:29], v[28:29]
	v_pk_add_f32 v[146:147], v[146:147], v[146:147] op_sel_hi:[0,1]
	v_pk_mul_f32 v[150:151], v[26:27], v[26:27]
	v_mul_f32_e32 v146, v22, v22
	v_pk_mov_b32 v[152:153], v[150:151], v[148:149] op_sel:[1,0]
	v_mov_b32_e32 v151, v149
	v_pk_add_f32 v[148:149], v[152:153], v[150:151]
	v_pk_fma_f32 v[150:151], v[22:23], v[22:23], v[146:147] op_sel_hi:[1,1,0]
	v_mul_f32_e32 v146, v24, v24
	v_pk_add_f32 v[148:149], v[148:149], v[148:149] op_sel_hi:[0,1]
	v_pk_fma_f32 v[152:153], v[24:25], v[24:25], v[146:147] op_sel_hi:[1,1,0]
	v_mul_f32_e32 v150, v18, v18
	v_mul_f32_e32 v152, v19, v19
	v_mul_f32_e32 v146, v20, v20
	v_mul_f32_e32 v148, v21, v21
	v_pk_add_f32 v[150:151], v[150:151], v[152:153]
	v_pk_add_f32 v[146:147], v[146:147], v[148:149]
	v_pk_mul_f32 v[160:161], v[190:191], v[160:161] op_sel_hi:[0,1]
	v_pk_add_f32 v[146:147], v[150:151], v[146:147]
	v_pk_mul_f32 v[158:159], v[190:191], v[158:159] op_sel_hi:[0,1]
	v_add_f32_e32 v146, v146, v147
	v_mov_b32_e32 v147, v146
	s_nop 1
	v_permlane16_swap_b32_e32 v147, v146
	v_cvt_pk_bf16_f32 v158, v158, v159
	v_cvt_pk_bf16_f32 v159, v160, v161
	global_store_dwordx2 v[198:199], v[158:159], off
	v_pk_mul_f32 v[156:157], v[190:191], v[156:157] op_sel_hi:[0,1]
	s_waitcnt lgkmcnt(0)
	v_add_f32_e32 v146, v146, v147
	v_mov_b32_e32 v147, v146
	s_nop 1
	v_permlane32_swap_b32_e32 v147, v146
	v_pk_mul_f32 v[154:155], v[190:191], v[154:155] op_sel_hi:[0,1]
	v_cvt_pk_bf16_f32 v154, v154, v155
	v_cvt_pk_bf16_f32 v155, v156, v157
	global_store_dwordx2 v[198:199], v[154:155], off offset:32
	s_waitcnt lgkmcnt(0)
	v_add_f32_e32 v146, v146, v147
	v_fmamk_f32 v146, v146, 0x3c800000, v229
	v_cmp_gt_f32_e32 vcc, s92, v146
	v_mul_f32_e32 v147, 0x4b800000, v146
	s_nop 0
	v_cndmask_b32_e32 v146, v146, v147, vcc
	v_rsq_f32_e32 v146, v146
	s_nop 0
	v_mul_f32_e32 v147, 0x45800000, v146
	v_cndmask_b32_e32 v158, v146, v147, vcc
	v_pk_mul_f32 v[146:147], v[30:31], v[158:159] op_sel_hi:[1,0]
	v_pk_mul_f32 v[148:149], v[32:33], v[158:159] op_sel_hi:[1,0]
	v_pk_mul_f32 v[150:151], v[142:143], v[146:147]
	v_pk_mul_f32 v[152:153], v[144:145], v[148:149]
	v_pk_mul_f32 v[146:147], v[26:27], v[158:159] op_sel_hi:[1,0]
	v_pk_mul_f32 v[148:149], v[28:29], v[158:159] op_sel_hi:[1,0]
	v_pk_mul_f32 v[154:155], v[22:23], v[158:159] op_sel_hi:[1,0]
	v_pk_mul_f32 v[156:157], v[24:25], v[158:159] op_sel_hi:[1,0]
	v_pk_mul_f32 v[198:199], v[18:19], v[158:159] op_sel_hi:[1,0]
	v_pk_mul_f32 v[158:159], v[20:21], v[158:159] op_sel_hi:[1,0]
	v_pk_mul_f32 v[148:149], v[140:141], v[148:149]
	v_pk_mul_f32 v[146:147], v[138:139], v[146:147]
	v_pk_mul_f32 v[156:157], v[136:137], v[156:157]
	v_pk_mul_f32 v[154:155], v[134:135], v[154:155]
	v_pk_mul_f32 v[160:161], v[132:133], v[158:159]
	v_pk_mul_f32 v[158:159], v[130:131], v[198:199]
	v_or_b32_e32 v198, 16, v186
	s_and_b64 vcc, exec, s[4:5]
	s_cbranch_vccnz .LBB0_295
	v_lshlrev_b32_e32 v173, 9, v198
	v_and_b32_e32 v200, 0x1be00, v173
	v_mov_b32_e32 v201, v0
	v_lshl_add_u64 v[200:201], v[196:197], 0, v[200:201]
	global_store_dwordx4 v[200:201], v[150:153], off nt
	global_store_dwordx4 v[200:201], v[146:149], off offset:64 nt
	global_store_dwordx4 v[200:201], v[154:157], off offset:128 nt
	global_store_dwordx4 v[200:201], v[158:161], off offset:192 nt

.LBB0_297:
	v_mov_b32_e32 v191, v190
	v_ashrrev_i32_e32 v199, 31, v198
	v_mov_b32_e32 v200, v190
	v_mov_b32_e32 v201, v190
	v_lshlrev_b64 v[198:199], s37, v[198:199]
	v_pk_mul_f32 v[148:149], v[200:201], v[148:149]
	v_pk_mul_f32 v[146:147], v[190:191], v[146:147]
	v_lshl_add_u64 v[198:199], v[192:193], 0, v[198:199]
	v_cvt_pk_bf16_f32 v146, v146, v147
	v_cvt_pk_bf16_f32 v147, v148, v149
	global_store_dwordx2 v[198:199], v[146:147], off offset:32
	v_pk_mul_f32 v[146:147], v[200:201], v[156:157]
	v_pk_mul_f32 v[148:149], v[190:191], v[154:155]
	v_pk_mul_f32 v[152:153], v[200:201], v[152:153]
	v_cvt_pk_bf16_f32 v148, v148, v149
	v_cvt_pk_bf16_f32 v149, v146, v147
	global_store_dwordx2 v[198:199], v[148:149], off offset:64
	v_pk_mul_f32 v[146:147], v[200:201], v[160:161]
	v_pk_mul_f32 v[148:149], v[190:191], v[158:159]
	v_pk_mul_f32 v[150:151], v[190:191], v[150:151]
	v_cvt_pk_bf16_f32 v148, v148, v149
	v_cvt_pk_bf16_f32 v149, v146, v147
	v_cvt_pk_bf16_f32 v150, v150, v151
	v_cvt_pk_bf16_f32 v151, v152, v153
	global_store_dwordx2 v[198:199], v[148:149], off offset:96
	v_pk_mul_f32 v[146:147], v[36:37], v[36:37]
	v_pk_mul_f32 v[148:149], v[34:35], v[34:35]
	global_store_dwordx2 v[198:199], v[150:151], off
	v_pk_mov_b32 v[150:151], v[148:149], v[146:147] op_sel:[1,0]
	v_mov_b32_e32 v149, v147
	v_pk_add_f32 v[146:147], v[150:151], v[148:149]
	v_pk_mul_f32 v[148:149], v[44:45], v[44:45]
	v_pk_add_f32 v[146:147], v[146:147], v[146:147] op_sel_hi:[0,1]
	v_pk_mul_f32 v[150:151], v[42:43], v[42:43]
	v_mul_f32_e32 v146, v46, v46
	v_pk_mov_b32 v[152:153], v[150:151], v[148:149] op_sel:[1,0]
	v_mov_b32_e32 v151, v149
	v_pk_add_f32 v[148:149], v[152:153], v[150:151]
	v_pk_fma_f32 v[150:151], v[46:47], v[46:47], v[146:147] op_sel_hi:[1,1,0]
	v_mul_f32_e32 v146, v48, v48
	v_pk_add_f32 v[148:149], v[148:149], v[148:149] op_sel_hi:[0,1]
	v_pk_fma_f32 v[152:153], v[48:49], v[48:49], v[146:147] op_sel_hi:[1,1,0]
	v_mul_f32_e32 v150, v38, v38
	v_mul_f32_e32 v152, v39, v39
	v_mul_f32_e32 v146, v40, v40
	v_mul_f32_e32 v148, v41, v41
	v_pk_add_f32 v[150:151], v[150:151], v[152:153]
	v_pk_add_f32 v[146:147], v[146:147], v[148:149]
	s_nop 0
	v_pk_add_f32 v[146:147], v[150:151], v[146:147]
	s_nop 0
	v_add_f32_e32 v146, v146, v147
	v_mov_b32_e32 v147, v146
	s_nop 1
	v_permlane16_swap_b32_e32 v147, v146
	s_waitcnt lgkmcnt(0)
	v_add_f32_e32 v146, v146, v147
	v_mov_b32_e32 v147, v146
	s_nop 1
	v_permlane32_swap_b32_e32 v147, v146
	s_waitcnt lgkmcnt(0)
	v_add_f32_e32 v146, v146, v147
	v_fmamk_f32 v146, v146, 0x3c800000, v229
	v_cmp_gt_f32_e32 vcc, s92, v146
	v_mul_f32_e32 v147, 0x4b800000, v146
	s_nop 0
	v_cndmask_b32_e32 v146, v146, v147, vcc
	v_rsq_f32_e32 v146, v146
	s_nop 0
	v_mul_f32_e32 v147, 0x45800000, v146
	v_cndmask_b32_e32 v158, v146, v147, vcc
	v_pk_mul_f32 v[146:147], v[34:35], v[158:159] op_sel_hi:[1,0]
	v_pk_mul_f32 v[148:149], v[36:37], v[158:159] op_sel_hi:[1,0]
	v_pk_mul_f32 v[150:151], v[142:143], v[146:147]
	v_pk_mul_f32 v[152:153], v[144:145], v[148:149]
	v_pk_mul_f32 v[146:147], v[42:43], v[158:159] op_sel_hi:[1,0]
	v_pk_mul_f32 v[148:149], v[44:45], v[158:159] op_sel_hi:[1,0]
	v_pk_mul_f32 v[154:155], v[46:47], v[158:159] op_sel_hi:[1,0]
	v_pk_mul_f32 v[156:157], v[48:49], v[158:159] op_sel_hi:[1,0]
	v_pk_mul_f32 v[198:199], v[38:39], v[158:159] op_sel_hi:[1,0]
	v_pk_mul_f32 v[158:159], v[40:41], v[158:159] op_sel_hi:[1,0]
	v_pk_mul_f32 v[148:149], v[140:141], v[148:149]
	v_pk_mul_f32 v[146:147], v[138:139], v[146:147]
	v_pk_mul_f32 v[156:157], v[136:137], v[156:157]
	v_pk_mul_f32 v[154:155], v[134:135], v[154:155]
	v_pk_mul_f32 v[160:161], v[132:133], v[158:159]
	v_pk_mul_f32 v[158:159], v[130:131], v[198:199]
	v_or_b32_e32 v198, 32, v186
	s_and_b64 vcc, exec, s[4:5]
	s_cbranch_vccnz .LBB0_299
	v_lshlrev_b32_e32 v173, 9, v198
	v_and_b32_e32 v200, 0x1de00, v173
	v_mov_b32_e32 v201, v0
	v_lshl_add_u64 v[200:201], v[196:197], 0, v[200:201]
	global_store_dwordx4 v[200:201], v[150:153], off nt
	global_store_dwordx4 v[200:201], v[146:149], off offset:64 nt
	global_store_dwordx4 v[200:201], v[154:157], off offset:128 nt
	global_store_dwordx4 v[200:201], v[158:161], off offset:192 nt

.LBB0_301:
	v_ashrrev_i32_e32 v199, 31, v198
	v_mov_b32_e32 v200, v190
	v_mov_b32_e32 v201, v190
	v_lshlrev_b64 v[198:199], s37, v[198:199]
	v_pk_mul_f32 v[148:149], v[200:201], v[148:149]
	v_pk_mul_f32 v[146:147], v[190:191], v[146:147]
	v_lshl_add_u64 v[198:199], v[192:193], 0, v[198:199]
	v_cvt_pk_bf16_f32 v146, v146, v147
	v_cvt_pk_bf16_f32 v147, v148, v149
	global_store_dwordx2 v[198:199], v[146:147], off offset:32
	v_pk_mul_f32 v[146:147], v[200:201], v[156:157]
	v_pk_mul_f32 v[148:149], v[190:191], v[154:155]
	v_pk_mul_f32 v[152:153], v[200:201], v[152:153]
	v_cvt_pk_bf16_f32 v148, v148, v149
	v_cvt_pk_bf16_f32 v149, v146, v147
	global_store_dwordx2 v[198:199], v[148:149], off offset:64
	v_pk_mul_f32 v[146:147], v[200:201], v[160:161]
	v_pk_mul_f32 v[148:149], v[190:191], v[158:159]
	v_pk_mul_f32 v[150:151], v[190:191], v[150:151]
	v_cvt_pk_bf16_f32 v148, v148, v149
	v_cvt_pk_bf16_f32 v149, v146, v147
	v_cvt_pk_bf16_f32 v150, v150, v151
	v_cvt_pk_bf16_f32 v151, v152, v153
	global_store_dwordx2 v[198:199], v[148:149], off offset:96
	v_pk_mul_f32 v[146:147], v[64:65], v[64:65]
	v_pk_mul_f32 v[148:149], v[62:63], v[62:63]
	global_store_dwordx2 v[198:199], v[150:151], off
	v_pk_mov_b32 v[150:151], v[148:149], v[146:147] op_sel:[1,0]
	v_mov_b32_e32 v149, v147
	v_pk_add_f32 v[146:147], v[150:151], v[148:149]
	v_pk_mul_f32 v[148:149], v[60:61], v[60:61]
	v_pk_add_f32 v[146:147], v[146:147], v[146:147] op_sel_hi:[0,1]
	v_pk_mul_f32 v[150:151], v[58:59], v[58:59]
	v_mul_f32_e32 v146, v54, v54
	v_pk_mov_b32 v[152:153], v[150:151], v[148:149] op_sel:[1,0]
	v_mov_b32_e32 v151, v149
	v_pk_add_f32 v[148:149], v[152:153], v[150:151]
	v_pk_fma_f32 v[150:151], v[54:55], v[54:55], v[146:147] op_sel_hi:[1,1,0]
	v_mul_f32_e32 v146, v56, v56
	v_pk_add_f32 v[148:149], v[148:149], v[148:149] op_sel_hi:[0,1]
	v_pk_fma_f32 v[152:153], v[56:57], v[56:57], v[146:147] op_sel_hi:[1,1,0]
	v_mul_f32_e32 v150, v50, v50
	v_mul_f32_e32 v152, v51, v51
	v_mul_f32_e32 v146, v52, v52
	v_mul_f32_e32 v148, v53, v53
	v_pk_add_f32 v[150:151], v[150:151], v[152:153]
	v_pk_add_f32 v[146:147], v[146:147], v[148:149]
	s_nop 0
	v_pk_add_f32 v[146:147], v[150:151], v[146:147]
	s_nop 0
	v_add_f32_e32 v146, v146, v147
	v_mov_b32_e32 v147, v146
	s_nop 1
	v_permlane16_swap_b32_e32 v147, v146
	s_waitcnt lgkmcnt(0)
	v_add_f32_e32 v146, v146, v147
	v_mov_b32_e32 v147, v146
	s_nop 1
	v_permlane32_swap_b32_e32 v147, v146
	s_waitcnt lgkmcnt(0)
	v_add_f32_e32 v146, v146, v147
	v_fmamk_f32 v146, v146, 0x3c800000, v229
	v_cmp_gt_f32_e32 vcc, s92, v146
	v_mul_f32_e32 v147, 0x4b800000, v146
	s_nop 0
	v_cndmask_b32_e32 v146, v146, v147, vcc
	v_rsq_f32_e32 v146, v146
	s_nop 0
	v_mul_f32_e32 v147, 0x45800000, v146
	v_cndmask_b32_e32 v146, v146, v147, vcc
	v_pk_mul_f32 v[148:149], v[62:63], v[146:147] op_sel_hi:[1,0]
	v_pk_mul_f32 v[150:151], v[64:65], v[146:147] op_sel_hi:[1,0]
	v_pk_mul_f32 v[158:159], v[142:143], v[148:149]
	v_pk_mul_f32 v[160:161], v[144:145], v[150:151]
	v_pk_mul_f32 v[148:149], v[58:59], v[146:147] op_sel_hi:[1,0]
	v_pk_mul_f32 v[150:151], v[60:61], v[146:147] op_sel_hi:[1,0]
	v_pk_mul_f32 v[154:155], v[138:139], v[148:149]
	v_pk_mul_f32 v[156:157], v[140:141], v[150:151]
	v_pk_mul_f32 v[148:149], v[54:55], v[146:147] op_sel_hi:[1,0]
	v_pk_mul_f32 v[150:151], v[56:57], v[146:147] op_sel_hi:[1,0]
	v_pk_mul_f32 v[198:199], v[50:51], v[146:147] op_sel_hi:[1,0]
	v_pk_mul_f32 v[146:147], v[52:53], v[146:147] op_sel_hi:[1,0]
	v_pk_mul_f32 v[152:153], v[136:137], v[150:151]
	v_pk_mul_f32 v[150:151], v[134:135], v[148:149]
	v_pk_mul_f32 v[148:149], v[132:133], v[146:147]
	v_pk_mul_f32 v[146:147], v[130:131], v[198:199]
	v_or_b32_e32 v198, 48, v186
	s_and_b64 vcc, exec, s[4:5]
	s_cbranch_vccnz .LBB0_303
	v_lshlrev_b32_e32 v173, 9, v198
	v_and_b32_e32 v200, 0x1fe00, v173
	v_mov_b32_e32 v201, v0
	v_lshl_add_u64 v[196:197], v[196:197], 0, v[200:201]
	global_store_dwordx4 v[196:197], v[158:161], off nt
	global_store_dwordx4 v[196:197], v[154:157], off offset:64 nt
	global_store_dwordx4 v[196:197], v[150:153], off offset:128 nt
	global_store_dwordx4 v[196:197], v[146:149], off offset:192 nt

.LBB0_305:
	v_ashrrev_i32_e32 v199, 31, v198
	v_lshlrev_b64 v[196:197], s37, v[198:199]
	v_mov_b32_e32 v198, v190
	v_mov_b32_e32 v199, v190
	v_pk_mul_f32 v[152:153], v[198:199], v[152:153]
	v_pk_mul_f32 v[150:151], v[190:191], v[150:151]
	v_lshl_add_u64 v[196:197], v[192:193], 0, v[196:197]
	v_pk_mul_f32 v[156:157], v[198:199], v[156:157]
	v_pk_mul_f32 v[154:155], v[190:191], v[154:155]
	v_cvt_pk_bf16_f32 v150, v150, v151
	v_cvt_pk_bf16_f32 v151, v152, v153
	v_cvt_pk_bf16_f32 v154, v154, v155
	v_cvt_pk_bf16_f32 v155, v156, v157
	global_store_dwordx2 v[196:197], v[150:151], off offset:64
	v_pk_mul_f32 v[150:151], v[76:77], v[76:77]
	v_pk_mul_f32 v[152:153], v[74:75], v[74:75]
	global_store_dwordx2 v[196:197], v[154:155], off offset:32
	v_pk_mov_b32 v[154:155], v[152:153], v[150:151] op_sel:[1,0]
	v_mov_b32_e32 v153, v151
	v_pk_add_f32 v[150:151], v[154:155], v[152:153]
	v_pk_mul_f32 v[152:153], v[72:73], v[72:73]
	v_pk_add_f32 v[150:151], v[150:151], v[150:151] op_sel_hi:[0,1]
	v_pk_mul_f32 v[154:155], v[70:71], v[70:71]
	v_mul_f32_e32 v150, v78, v78
	v_pk_mov_b32 v[156:157], v[154:155], v[152:153] op_sel:[1,0]
	v_mov_b32_e32 v155, v153
	v_pk_add_f32 v[152:153], v[156:157], v[154:155]
	v_pk_fma_f32 v[154:155], v[78:79], v[78:79], v[150:151] op_sel_hi:[1,1,0]
	v_mul_f32_e32 v150, v80, v80
	v_pk_add_f32 v[152:153], v[152:153], v[152:153] op_sel_hi:[0,1]
	v_pk_fma_f32 v[156:157], v[80:81], v[80:81], v[150:151] op_sel_hi:[1,1,0]
	v_mul_f32_e32 v154, v66, v66
	v_mul_f32_e32 v156, v67, v67
	v_mul_f32_e32 v150, v68, v68
	v_mul_f32_e32 v152, v69, v69
	v_pk_add_f32 v[154:155], v[154:155], v[156:157]
	v_pk_add_f32 v[150:151], v[150:151], v[152:153]
	v_pk_mul_f32 v[148:149], v[198:199], v[148:149]
	v_pk_add_f32 v[150:151], v[154:155], v[150:151]
	v_pk_mul_f32 v[146:147], v[190:191], v[146:147]
	v_add_f32_e32 v150, v150, v151
	v_mov_b32_e32 v151, v150
	s_nop 1
	v_permlane16_swap_b32_e32 v151, v150
	v_cvt_pk_bf16_f32 v146, v146, v147
	v_cvt_pk_bf16_f32 v147, v148, v149
	global_store_dwordx2 v[196:197], v[146:147], off offset:96
	v_pk_mul_f32 v[160:161], v[198:199], v[160:161]
	s_waitcnt lgkmcnt(0)
	v_add_f32_e32 v148, v150, v151
	v_mov_b32_e32 v149, v148
	s_nop 1
	v_permlane32_swap_b32_e32 v149, v148
	v_pk_mul_f32 v[158:159], v[190:191], v[158:159]
	s_waitcnt lgkmcnt(0)
	v_add_f32_e32 v147, v148, v149
	v_fmamk_f32 v147, v147, 0x3c800000, v229
	v_cvt_pk_bf16_f32 v158, v158, v159
	v_cvt_pk_bf16_f32 v159, v160, v161
	v_mul_f32_e32 v148, 0x4b800000, v147
	v_cmp_gt_f32_e32 vcc, s92, v147
	global_store_dwordx2 v[196:197], v[158:159], off
	v_add_u32_e32 v196, 0x80, v186
	v_cndmask_b32_e32 v147, v147, v148, vcc
	v_ashrrev_i32_e32 v146, 7, v196
	v_rsq_f32_e32 v148, v147
	v_and_or_b32 v146, v146, -2, v179
	v_ashrrev_i32_e32 v147, 31, v146
	v_lshlrev_b64 v[146:147], 17, v[146:147]
	v_lshl_add_u64 v[194:195], v[194:195], 0, v[146:147]
	v_mul_f32_e32 v146, 0x45800000, v148
	v_cndmask_b32_e32 v158, v148, v146, vcc
	v_pk_mul_f32 v[146:147], v[74:75], v[158:159] op_sel_hi:[1,0]
	v_pk_mul_f32 v[148:149], v[76:77], v[158:159] op_sel_hi:[1,0]
	v_pk_mul_f32 v[150:151], v[142:143], v[146:147]
	v_pk_mul_f32 v[152:153], v[144:145], v[148:149]
	v_pk_mul_f32 v[146:147], v[70:71], v[158:159] op_sel_hi:[1,0]
	v_pk_mul_f32 v[148:149], v[72:73], v[158:159] op_sel_hi:[1,0]
	v_pk_mul_f32 v[154:155], v[78:79], v[158:159] op_sel_hi:[1,0]
	v_pk_mul_f32 v[156:157], v[80:81], v[158:159] op_sel_hi:[1,0]
	v_pk_mul_f32 v[198:199], v[66:67], v[158:159] op_sel_hi:[1,0]
	v_pk_mul_f32 v[158:159], v[68:69], v[158:159] op_sel_hi:[1,0]
	v_pk_mul_f32 v[148:149], v[140:141], v[148:149]
	v_pk_mul_f32 v[146:147], v[138:139], v[146:147]
	v_pk_mul_f32 v[156:157], v[136:137], v[156:157]
	v_pk_mul_f32 v[154:155], v[134:135], v[154:155]
	v_pk_mul_f32 v[160:161], v[132:133], v[158:159]
	s_and_b64 vcc, exec, s[4:5]
	v_pk_mul_f32 v[158:159], v[130:131], v[198:199]
	s_cbranch_vccnz .LBB0_307
	v_lshlrev_b32_e32 v173, 9, v196
	v_and_b32_e32 v198, 0x19e00, v173
	v_mov_b32_e32 v199, v0
	v_lshl_add_u64 v[198:199], v[194:195], 0, v[198:199]
	global_store_dwordx4 v[198:199], v[150:153], off nt
	global_store_dwordx4 v[198:199], v[146:149], off offset:64 nt
	global_store_dwordx4 v[198:199], v[154:157], off offset:128 nt
	global_store_dwordx4 v[198:199], v[158:161], off offset:192 nt

.LBB0_309:
	v_ashrrev_i32_e32 v197, 31, v196
	v_mov_b32_e32 v198, v190
	v_mov_b32_e32 v199, v190
	v_lshlrev_b64 v[196:197], s37, v[196:197]
	v_pk_mul_f32 v[148:149], v[198:199], v[148:149]
	v_pk_mul_f32 v[146:147], v[190:191], v[146:147]
	v_lshl_add_u64 v[196:197], v[192:193], 0, v[196:197]
	v_cvt_pk_bf16_f32 v146, v146, v147
	v_cvt_pk_bf16_f32 v147, v148, v149
	global_store_dwordx2 v[196:197], v[146:147], off offset:32
	v_pk_mul_f32 v[146:147], v[198:199], v[156:157]
	v_pk_mul_f32 v[148:149], v[190:191], v[154:155]
	v_pk_mul_f32 v[152:153], v[198:199], v[152:153]
	v_cvt_pk_bf16_f32 v148, v148, v149
	v_cvt_pk_bf16_f32 v149, v146, v147
	global_store_dwordx2 v[196:197], v[148:149], off offset:64
	v_pk_mul_f32 v[146:147], v[198:199], v[160:161]
	v_pk_mul_f32 v[148:149], v[190:191], v[158:159]
	v_pk_mul_f32 v[150:151], v[190:191], v[150:151]
	v_cvt_pk_bf16_f32 v148, v148, v149
	v_cvt_pk_bf16_f32 v149, v146, v147
	v_cvt_pk_bf16_f32 v150, v150, v151
	v_cvt_pk_bf16_f32 v151, v152, v153
	global_store_dwordx2 v[196:197], v[148:149], off offset:96
	v_pk_mul_f32 v[146:147], v[96:97], v[96:97]
	v_pk_mul_f32 v[148:149], v[94:95], v[94:95]
	global_store_dwordx2 v[196:197], v[150:151], off
	v_pk_mov_b32 v[150:151], v[148:149], v[146:147] op_sel:[1,0]
	v_mov_b32_e32 v149, v147
	v_pk_add_f32 v[146:147], v[150:151], v[148:149]
	v_pk_mul_f32 v[148:149], v[92:93], v[92:93]
	v_pk_add_f32 v[146:147], v[146:147], v[146:147] op_sel_hi:[0,1]
	v_pk_mul_f32 v[150:151], v[90:91], v[90:91]
	v_mul_f32_e32 v146, v86, v86
	v_pk_mov_b32 v[152:153], v[150:151], v[148:149] op_sel:[1,0]
	v_mov_b32_e32 v151, v149
	v_pk_add_f32 v[148:149], v[152:153], v[150:151]
	v_pk_fma_f32 v[150:151], v[86:87], v[86:87], v[146:147] op_sel_hi:[1,1,0]
	v_mul_f32_e32 v146, v88, v88
	v_pk_add_f32 v[148:149], v[148:149], v[148:149] op_sel_hi:[0,1]
	v_pk_fma_f32 v[152:153], v[88:89], v[88:89], v[146:147] op_sel_hi:[1,1,0]
	v_mul_f32_e32 v150, v82, v82
	v_mul_f32_e32 v152, v83, v83
	v_mul_f32_e32 v146, v84, v84
	v_mul_f32_e32 v148, v85, v85
	v_pk_add_f32 v[150:151], v[150:151], v[152:153]
	v_pk_add_f32 v[146:147], v[146:147], v[148:149]
	s_nop 0
	v_pk_add_f32 v[146:147], v[150:151], v[146:147]
	s_nop 0
	v_add_f32_e32 v146, v146, v147
	v_mov_b32_e32 v147, v146
	s_nop 1
	v_permlane16_swap_b32_e32 v147, v146
	s_waitcnt lgkmcnt(0)
	v_add_f32_e32 v146, v146, v147
	v_mov_b32_e32 v147, v146
	s_nop 1
	v_permlane32_swap_b32_e32 v147, v146
	s_waitcnt lgkmcnt(0)
	v_add_f32_e32 v146, v146, v147
	v_fmamk_f32 v146, v146, 0x3c800000, v229
	v_cmp_gt_f32_e32 vcc, s92, v146
	v_mul_f32_e32 v147, 0x4b800000, v146
	s_nop 0
	v_cndmask_b32_e32 v146, v146, v147, vcc
	v_rsq_f32_e32 v146, v146
	s_nop 0
	v_mul_f32_e32 v147, 0x45800000, v146
	v_cndmask_b32_e32 v158, v146, v147, vcc
	v_pk_mul_f32 v[146:147], v[94:95], v[158:159] op_sel_hi:[1,0]
	v_pk_mul_f32 v[148:149], v[96:97], v[158:159] op_sel_hi:[1,0]
	v_pk_mul_f32 v[150:151], v[142:143], v[146:147]
	v_pk_mul_f32 v[152:153], v[144:145], v[148:149]
	v_pk_mul_f32 v[146:147], v[90:91], v[158:159] op_sel_hi:[1,0]
	v_pk_mul_f32 v[148:149], v[92:93], v[158:159] op_sel_hi:[1,0]
	v_pk_mul_f32 v[154:155], v[86:87], v[158:159] op_sel_hi:[1,0]
	v_pk_mul_f32 v[156:157], v[88:89], v[158:159] op_sel_hi:[1,0]
	v_pk_mul_f32 v[196:197], v[82:83], v[158:159] op_sel_hi:[1,0]
	v_pk_mul_f32 v[158:159], v[84:85], v[158:159] op_sel_hi:[1,0]
	v_pk_mul_f32 v[148:149], v[140:141], v[148:149]
	v_pk_mul_f32 v[146:147], v[138:139], v[146:147]
	v_pk_mul_f32 v[156:157], v[136:137], v[156:157]
	v_pk_mul_f32 v[154:155], v[134:135], v[154:155]
	v_pk_mul_f32 v[160:161], v[132:133], v[158:159]
	v_pk_mul_f32 v[158:159], v[130:131], v[196:197]
	v_add_u32_e32 v196, 0x90, v186
	s_and_b64 vcc, exec, s[4:5]
	s_cbranch_vccnz .LBB0_311
	v_lshlrev_b32_e32 v171, 9, v196
	v_and_b32_e32 v198, 0x1be00, v171
	v_mov_b32_e32 v199, v0
	v_lshl_add_u64 v[198:199], v[194:195], 0, v[198:199]
	global_store_dwordx4 v[198:199], v[150:153], off nt
	global_store_dwordx4 v[198:199], v[146:149], off offset:64 nt
	global_store_dwordx4 v[198:199], v[154:157], off offset:128 nt
	global_store_dwordx4 v[198:199], v[158:161], off offset:192 nt

.LBB0_313:
	v_ashrrev_i32_e32 v197, 31, v196
	v_mov_b32_e32 v198, v190
	v_mov_b32_e32 v199, v190
	v_lshlrev_b64 v[196:197], s37, v[196:197]
	v_pk_mul_f32 v[148:149], v[198:199], v[148:149]
	v_pk_mul_f32 v[146:147], v[190:191], v[146:147]
	v_lshl_add_u64 v[196:197], v[192:193], 0, v[196:197]
	v_cvt_pk_bf16_f32 v146, v146, v147
	v_cvt_pk_bf16_f32 v147, v148, v149
	global_store_dwordx2 v[196:197], v[146:147], off offset:32
	v_pk_mul_f32 v[146:147], v[198:199], v[156:157]
	v_pk_mul_f32 v[148:149], v[190:191], v[154:155]
	v_pk_mul_f32 v[152:153], v[198:199], v[152:153]
	v_cvt_pk_bf16_f32 v148, v148, v149
	v_cvt_pk_bf16_f32 v149, v146, v147
	global_store_dwordx2 v[196:197], v[148:149], off offset:64
	v_pk_mul_f32 v[146:147], v[198:199], v[160:161]
	v_pk_mul_f32 v[148:149], v[190:191], v[158:159]
	v_pk_mul_f32 v[150:151], v[190:191], v[150:151]
	v_cvt_pk_bf16_f32 v148, v148, v149
	v_cvt_pk_bf16_f32 v149, v146, v147
	v_cvt_pk_bf16_f32 v150, v150, v151
	v_cvt_pk_bf16_f32 v151, v152, v153
	global_store_dwordx2 v[196:197], v[148:149], off offset:96
	v_pk_mul_f32 v[146:147], v[108:109], v[108:109]
	v_pk_mul_f32 v[148:149], v[106:107], v[106:107]
	global_store_dwordx2 v[196:197], v[150:151], off
	v_pk_mov_b32 v[150:151], v[148:149], v[146:147] op_sel:[1,0]
	v_mov_b32_e32 v149, v147
	v_pk_add_f32 v[146:147], v[150:151], v[148:149]
	v_pk_mul_f32 v[148:149], v[104:105], v[104:105]
	v_pk_add_f32 v[146:147], v[146:147], v[146:147] op_sel_hi:[0,1]
	v_pk_mul_f32 v[150:151], v[102:103], v[102:103]
	v_mul_f32_e32 v146, v110, v110
	v_pk_mov_b32 v[152:153], v[150:151], v[148:149] op_sel:[1,0]
	v_mov_b32_e32 v151, v149
	v_pk_add_f32 v[148:149], v[152:153], v[150:151]
	v_pk_fma_f32 v[150:151], v[110:111], v[110:111], v[146:147] op_sel_hi:[1,1,0]
	v_mul_f32_e32 v146, v112, v112
	v_pk_add_f32 v[148:149], v[148:149], v[148:149] op_sel_hi:[0,1]
	v_pk_fma_f32 v[152:153], v[112:113], v[112:113], v[146:147] op_sel_hi:[1,1,0]
	v_mul_f32_e32 v150, v98, v98
	v_mul_f32_e32 v152, v99, v99
	v_mul_f32_e32 v146, v100, v100
	v_mul_f32_e32 v148, v101, v101
	v_pk_add_f32 v[150:151], v[150:151], v[152:153]
	v_pk_add_f32 v[146:147], v[146:147], v[148:149]
	s_nop 0
	v_pk_add_f32 v[146:147], v[150:151], v[146:147]
	s_nop 0
	v_add_f32_e32 v146, v146, v147
	v_mov_b32_e32 v147, v146
	s_nop 1
	v_permlane16_swap_b32_e32 v147, v146
	s_waitcnt lgkmcnt(0)
	v_add_f32_e32 v146, v146, v147
	v_mov_b32_e32 v147, v146
	s_nop 1
	v_permlane32_swap_b32_e32 v147, v146
	s_waitcnt lgkmcnt(0)
	v_add_f32_e32 v146, v146, v147
	v_fmamk_f32 v146, v146, 0x3c800000, v229
	v_cmp_gt_f32_e32 vcc, s92, v146
	v_mul_f32_e32 v147, 0x4b800000, v146
	s_nop 0
	v_cndmask_b32_e32 v146, v146, v147, vcc
	v_rsq_f32_e32 v146, v146
	s_nop 0
	v_mul_f32_e32 v147, 0x45800000, v146
	v_cndmask_b32_e32 v158, v146, v147, vcc
	v_pk_mul_f32 v[146:147], v[106:107], v[158:159] op_sel_hi:[1,0]
	v_pk_mul_f32 v[148:149], v[108:109], v[158:159] op_sel_hi:[1,0]
	v_pk_mul_f32 v[150:151], v[142:143], v[146:147]
	v_pk_mul_f32 v[152:153], v[144:145], v[148:149]
	v_pk_mul_f32 v[146:147], v[102:103], v[158:159] op_sel_hi:[1,0]
	v_pk_mul_f32 v[148:149], v[104:105], v[158:159] op_sel_hi:[1,0]
	v_pk_mul_f32 v[154:155], v[110:111], v[158:159] op_sel_hi:[1,0]
	v_pk_mul_f32 v[156:157], v[112:113], v[158:159] op_sel_hi:[1,0]
	v_pk_mul_f32 v[196:197], v[98:99], v[158:159] op_sel_hi:[1,0]
	v_pk_mul_f32 v[158:159], v[100:101], v[158:159] op_sel_hi:[1,0]
	v_pk_mul_f32 v[148:149], v[140:141], v[148:149]
	v_pk_mul_f32 v[146:147], v[138:139], v[146:147]
	v_pk_mul_f32 v[156:157], v[136:137], v[156:157]
	v_pk_mul_f32 v[154:155], v[134:135], v[154:155]
	v_pk_mul_f32 v[160:161], v[132:133], v[158:159]
	v_pk_mul_f32 v[158:159], v[130:131], v[196:197]
	v_add_u32_e32 v196, 0xa0, v186
	s_and_b64 vcc, exec, s[4:5]
	s_cbranch_vccnz .LBB0_315
	v_lshlrev_b32_e32 v171, 9, v196
	v_and_b32_e32 v198, 0x1de00, v171
	v_mov_b32_e32 v199, v0
	v_lshl_add_u64 v[198:199], v[194:195], 0, v[198:199]
	global_store_dwordx4 v[198:199], v[150:153], off nt
	global_store_dwordx4 v[198:199], v[146:149], off offset:64 nt
	global_store_dwordx4 v[198:199], v[154:157], off offset:128 nt
	global_store_dwordx4 v[198:199], v[158:161], off offset:192 nt

.LBB0_317:
	v_ashrrev_i32_e32 v197, 31, v196
	v_mov_b32_e32 v198, v190
	v_mov_b32_e32 v199, v190
	v_lshlrev_b64 v[196:197], s37, v[196:197]
	v_pk_mul_f32 v[148:149], v[198:199], v[148:149]
	v_pk_mul_f32 v[146:147], v[190:191], v[146:147]
	v_lshl_add_u64 v[196:197], v[192:193], 0, v[196:197]
	v_cvt_pk_bf16_f32 v146, v146, v147
	v_cvt_pk_bf16_f32 v147, v148, v149
	global_store_dwordx2 v[196:197], v[146:147], off offset:32
	v_pk_mul_f32 v[146:147], v[198:199], v[156:157]
	v_pk_mul_f32 v[148:149], v[190:191], v[154:155]
	v_pk_mul_f32 v[152:153], v[198:199], v[152:153]
	v_cvt_pk_bf16_f32 v148, v148, v149
	v_cvt_pk_bf16_f32 v149, v146, v147
	global_store_dwordx2 v[196:197], v[148:149], off offset:64
	v_pk_mul_f32 v[146:147], v[198:199], v[160:161]
	v_pk_mul_f32 v[148:149], v[190:191], v[158:159]
	v_pk_mul_f32 v[150:151], v[190:191], v[150:151]
	v_cvt_pk_bf16_f32 v148, v148, v149
	v_cvt_pk_bf16_f32 v149, v146, v147
	v_cvt_pk_bf16_f32 v150, v150, v151
	v_cvt_pk_bf16_f32 v151, v152, v153
	global_store_dwordx2 v[196:197], v[148:149], off offset:96
	v_pk_mul_f32 v[146:147], v[120:121], v[120:121]
	v_pk_mul_f32 v[148:149], v[118:119], v[118:119]
	global_store_dwordx2 v[196:197], v[150:151], off
	v_pk_mov_b32 v[150:151], v[148:149], v[146:147] op_sel:[1,0]
	v_mov_b32_e32 v149, v147
	v_pk_add_f32 v[146:147], v[150:151], v[148:149]
	v_pk_mul_f32 v[148:149], v[116:117], v[116:117]
	v_pk_add_f32 v[146:147], v[146:147], v[146:147] op_sel_hi:[0,1]
	v_pk_mul_f32 v[150:151], v[114:115], v[114:115]
	v_mul_f32_e32 v146, v122, v122
	v_pk_mov_b32 v[152:153], v[150:151], v[148:149] op_sel:[1,0]
	v_mov_b32_e32 v151, v149
	v_pk_add_f32 v[148:149], v[152:153], v[150:151]
	v_pk_fma_f32 v[150:151], v[122:123], v[122:123], v[146:147] op_sel_hi:[1,1,0]
	v_mul_f32_e32 v146, v124, v124
	v_pk_add_f32 v[148:149], v[148:149], v[148:149] op_sel_hi:[0,1]
	v_pk_fma_f32 v[152:153], v[124:125], v[124:125], v[146:147] op_sel_hi:[1,1,0]
	v_mul_f32_e32 v150, v126, v126
	v_mul_f32_e32 v152, v127, v127
	v_mul_f32_e32 v146, v128, v128
	v_mul_f32_e32 v148, v129, v129
	v_pk_add_f32 v[150:151], v[150:151], v[152:153]
	v_pk_add_f32 v[146:147], v[146:147], v[148:149]
	s_nop 0
	v_pk_add_f32 v[146:147], v[150:151], v[146:147]
	s_nop 0
	v_add_f32_e32 v146, v146, v147
	v_mov_b32_e32 v147, v146
	s_nop 1
	v_permlane16_swap_b32_e32 v147, v146
	s_waitcnt lgkmcnt(0)
	v_add_f32_e32 v146, v146, v147
	v_mov_b32_e32 v147, v146
	s_nop 1
	v_permlane32_swap_b32_e32 v147, v146
	s_waitcnt lgkmcnt(0)
	v_add_f32_e32 v146, v146, v147
	v_fmamk_f32 v146, v146, 0x3c800000, v229
	v_cmp_gt_f32_e32 vcc, s92, v146
	v_mul_f32_e32 v147, 0x4b800000, v146
	s_nop 0
	v_cndmask_b32_e32 v146, v146, v147, vcc
	v_rsq_f32_e32 v146, v146
	s_nop 0
	v_mul_f32_e32 v147, 0x45800000, v146
	v_cndmask_b32_e32 v146, v146, v147, vcc
	v_pk_mul_f32 v[148:149], v[118:119], v[146:147] op_sel_hi:[1,0]
	v_pk_mul_f32 v[150:151], v[120:121], v[146:147] op_sel_hi:[1,0]
	v_pk_mul_f32 v[142:143], v[142:143], v[148:149]
	v_pk_mul_f32 v[148:149], v[114:115], v[146:147] op_sel_hi:[1,0]
	v_pk_mul_f32 v[144:145], v[144:145], v[150:151]
	v_pk_mul_f32 v[150:151], v[116:117], v[146:147] op_sel_hi:[1,0]
	v_pk_mul_f32 v[138:139], v[138:139], v[148:149]
	v_pk_mul_f32 v[148:149], v[122:123], v[146:147] op_sel_hi:[1,0]
	v_pk_mul_f32 v[140:141], v[140:141], v[150:151]
	v_pk_mul_f32 v[150:151], v[124:125], v[146:147] op_sel_hi:[1,0]
	v_pk_mul_f32 v[134:135], v[134:135], v[148:149]
	v_pk_mul_f32 v[148:149], v[126:127], v[146:147] op_sel_hi:[1,0]
	v_pk_mul_f32 v[146:147], v[128:129], v[146:147] op_sel_hi:[1,0]
	v_pk_mul_f32 v[136:137], v[136:137], v[150:151]
	v_pk_mul_f32 v[132:133], v[132:133], v[146:147]
	v_pk_mul_f32 v[130:131], v[130:131], v[148:149]
	v_add_u32_e32 v146, 0xb0, v186
	s_and_b64 vcc, exec, s[4:5]
	s_cbranch_vccnz .LBB0_319
	v_lshlrev_b32_e32 v147, 9, v146
	v_and_b32_e32 v148, 0x1fe00, v147
	v_mov_b32_e32 v149, v0
	v_lshl_add_u64 v[148:149], v[194:195], 0, v[148:149]
	global_store_dwordx4 v[148:149], v[142:145], off nt
	global_store_dwordx4 v[148:149], v[138:141], off offset:64 nt
	global_store_dwordx4 v[148:149], v[134:137], off offset:128 nt
	global_store_dwordx4 v[148:149], v[130:133], off offset:192 nt
